# deferred L1 ConvFFN weight conversion rebalanced at item granularity: XA steps convert exactly 15 items per wave (4800 per segment half), remainder 3x1408 items in the balanced prologue
# baseline (speedup 1.0000x reference)
; #define LAS __attribute__((address_space(3)))
; __device__ __forceinline__ void convert_segments(const Args& args, unsigned char* ws, LAS unsigned char* lds, int seg_lo, int seg_hi, int part_lo, int part_hi, int nparts, int wid, int nw, int wave, int lane) {
;     LAS float* scr = (LAS float*)(lds + wave * 16640);
; #pragma unroll 1
;     for (int sI = seg_lo; sI < seg_hi; ++sI) {
;         const Seg sg = seg_at(sI);
;         const int nblk = sg.ncols / 64, nit = (sg.K / 64) * nblk;
;         const float* W = args.in[sg.in_idx] + (size_t)sg.src_l * sg.K * sg.N;
;         bf16* WT = (bf16*)(ws + WS_W + (size_t)sg.layer * LAYER_W + (size_t)sg.wsub_mib * MiB);
;         const int it_lo = (int)((long)nit * part_lo / nparts), it_hi = (int)((long)nit * part_hi / nparts);
;         int it = it_lo + wid;
;         f32x4 v[16];
.LBB0_11:
	s_or_b64 exec, exec, s[4:5]
	s_load_dwordx2 s[36:37], s[0:1], 0xf0
	v_readlane_b32 s4, v254, 0
	s_lshr_b32 s89, s3, 6
	s_lshl_b32 s4, s4, 3
	s_lshl_b32 s38, s88, 3
	s_add_i32 s40, s4, s89
	s_waitcnt lgkmcnt(0)
	s_cmp_lt_i32 s36, 1
	s_cselect_b64 s[4:5], -1, 0
	s_cmp_gt_i32 s37, 0
	s_cselect_b64 s[6:7], -1, 0
	s_and_b64 s[4:5], s[4:5], s[6:7]
	s_andn2_b64 vcc, exec, s[4:5]
	s_cbranch_vccnz .LBB0_49
	s_mov_b64 s[12:13], 0
	s_load_dwordx2 s[14:15], s[0:1], 0xe8
	s_mul_i32 s4, s89, 0x4100
	v_mbcnt_lo_u32_b32 v65, -1, 0
	v_mbcnt_hi_u32_b32 v65, -1, v65
	s_mov_b32 s21, 0
	v_lshlrev_b32_e32 v0, 3, v65
	s_waitcnt lgkmcnt(0)
	s_add_u32 s5, s14, s12
	s_addc_u32 s6, s15, s13
	s_cmpk_eq_i32 s88, 0x100
	s_mov_b32 s19, 26
	s_add_i32 s4, s4, 0
	s_add_u32 s24, s5, 0x2d400000
	v_ashrrev_i32_e32 v66, 4, v65
	v_lshlrev_b32_e32 v64, 2, v65
	s_movk_i32 s5, 0x104
	v_ashrrev_i32_e32 v102, 3, v65
	v_and_b32_e32 v0, 56, v0
	v_and_b32_e32 v68, 60, v64
	v_mul_lo_u32 v2, v66, s5
	v_mul_u32_u24_e32 v3, 0x104, v0
	v_lshlrev_b32_e32 v4, 2, v102
	v_readlane_b32 s5, v254, 0
	s_addc_u32 s25, s6, 0
	v_lshl_add_u32 v1, v68, 2, s4
	v_add3_u32 v67, s4, v3, v4
	s_lshl_b32 s27, s5, 9
	s_lshl_b32 s4, s89, 6
	s_add_i32 s27, s27, s4
	s_lshl_b32 s39, s5, 10
	s_lshl_b32 s4, s89, 7
	v_mov_b32_e32 v71, 0
	v_add_u32_e32 v72, 4, v66
	v_add_u32_e32 v74, 8, v66
	v_add_u32_e32 v76, 12, v66
	v_add_u32_e32 v78, 16, v66
	v_add_u32_e32 v80, 20, v66
	v_add_u32_e32 v82, 24, v66
	v_add_u32_e32 v84, 28, v66
	v_add_u32_e32 v86, 32, v66
	v_add_u32_e32 v88, 36, v66
	v_add_u32_e32 v90, 40, v66
	v_add_u32_e32 v92, 44, v66
	v_add_u32_e32 v94, 48, v66
	v_add_u32_e32 v96, 52, v66
	v_add_u32_e32 v98, 56, v66
	v_add_u32_e32 v100, 60, v66
	v_add_u32_e32 v104, 8, v102
	v_add_u32_e32 v106, 16, v102
	v_add_u32_e32 v108, 24, v102
	v_add_u32_e32 v110, 32, v102
	v_add_u32_e32 v112, 40, v102
	v_add_u32_e32 v114, 48, v102
	v_add_u32_e32 v116, 56, v102
	s_ashr_i32 s41, s40, 31
	s_abs_i32 s26, s40
	s_lshl_b32 s18, s88, 9
	s_add_i32 s39, s39, s4
	s_lshl_b32 s42, s88, 10
	v_add_u32_e32 v69, v1, v2
	v_lshlrev_b32_e32 v70, 1, v0
	s_mov_b32 s43, 0
	s_mov_b32 s99, 0
	s_branch .LBB0_14

; __device__ __forceinline__ void convert_segments(const Args& args, unsigned char* ws, LAS unsigned char* lds, int seg_lo, int seg_hi, int part_lo, int part_hi, int nparts, int wid, int nw, int wave, int lane) {
;     ...
;     for (int sI = seg_lo; sI < seg_hi; ++sI) {
;         const Seg sg = seg_at(sI);
;         const int nblk = sg.ncols / 64, nit = (sg.K / 64) * nblk;
;         const float* W = args.in[sg.in_idx] + (size_t)sg.src_l * sg.K * sg.N;
;         bf16* WT = (bf16*)(ws + WS_W + (size_t)sg.layer * LAYER_W + (size_t)sg.wsub_mib * MiB);
;         const int it_lo = (int)((long)nit * part_lo / nparts), it_hi = (int)((long)nit * part_hi / nparts);
;         int it = it_lo + wid;
;         f32x4 v[16];
;         if (it < it_hi) { const int kb = it / nblk, nb = it - kb * nblk; tr_load(W + (size_t)(64 * kb) * sg.N + sg.scol + 64 * nb, sg.N, v, lane); }
.LBB0_14:
	s_mul_i32 s7, s43, 40
	s_getpc_b64 s[4:5]
	s_add_u32 s4, s4, __const._Z6seg_ati.segs@rel32@lo+4
	s_addc_u32 s5, s5, __const._Z6seg_ati.segs@rel32@hi+12
	s_mul_hi_u32 s6, s43, 40
	s_add_u32 s22, s4, s7
	s_addc_u32 s23, s5, s6
	s_load_dwordx8 s[4:11], s[22:23], 0x0
	v_lshlrev_b32_e32 v118, 2, v68
	s_waitcnt lgkmcnt(0)
	s_ashr_i32 s20, s9, 31
	s_ashr_i32 s48, s7, 31
	s_lshr_b32 s20, s20, 26
	s_lshr_b32 s44, s48, 26
	s_add_i32 s9, s9, s20
	s_ashr_i32 s51, s9, 6
	s_add_i32 s9, s7, s44
	s_ashr_i32 s47, s4, 31
	s_mov_b32 s46, s4
	s_ashr_i32 s9, s9, 6
	s_lshl_b64 s[46:47], s[46:47], 3
	s_add_u32 s46, s0, s46
	s_addc_u32 s47, s1, s47
	s_mul_i32 s44, s51, s9
	s_load_dwordx2 s[46:47], s[46:47], 0x0
	s_mul_i32 s9, s6, s5
	s_mul_hi_i32 s4, s6, s5
	s_mul_i32 s5, s9, s48
	s_mul_hi_u32 s20, s9, s7
	s_add_i32 s5, s20, s5
	s_mul_i32 s4, s4, s7
	s_add_i32 s5, s5, s4
	s_mul_i32 s4, s9, s7
	s_lshl_b64 s[4:5], s[4:5], 2
	s_waitcnt lgkmcnt(0)
	s_add_u32 s46, s46, s4
	s_addc_u32 s47, s47, s5
	s_add_i32 s98, s40, s99
	s_cmp_ge_u32 s98, s38
	s_cselect_b32 s100, s38, 0
	s_sub_i32 s98, s98, s100
	s_cmpk_eq_i32 s88, 0x100
	s_cselect_b32 s100, 0x7ff, 0
	s_cselect_b32 s101, 9600, 0
	s_cmp_lt_u32 s43, 23
	s_cselect_b32 s101, 0, s101
	s_add_i32 s98, s98, s101
	s_sub_i32 s99, s99, s44
	s_add_i32 s99, s99, s101
	s_and_b32 s99, s99, s100
	s_cmp_lt_i32 s98, s44
	s_mov_b32 s45, s7
	s_cselect_b64 s[4:5], -1, 0
	s_cmp_ge_i32 s98, s44
	s_cbranch_scc1 .LBB0_16
	s_abs_i32 s7, s51
	s_waitcnt vmcnt(15)
	v_cvt_f32_u32_e32 v0, s7
	s_sub_i32 s20, 0, s7
	s_ashr_i32 s9, s51, 31
	s_xor_b32 s9, s41, s9
	v_rcp_iflag_f32_e32 v0, v0
	v_mov_b32_e32 v119, v71
	v_mul_f32_e32 v0, 0x4f7ffffe, v0
	v_cvt_u32_f32_e32 v0, v0
	s_nop 0
	v_readfirstlane_b32 s48, v0
	s_mul_i32 s20, s20, s48
	s_mul_hi_u32 s20, s48, s20
	s_add_i32 s48, s48, s20
	s_mul_hi_u32 s20, s98, s48
	s_mul_i32 s48, s20, s7
	s_sub_i32 s48, s98, s48
	s_add_i32 s49, s20, 1
	s_sub_i32 s50, s48, s7
	s_cmp_ge_u32 s48, s7
	s_cselect_b32 s20, s49, s20
	s_cselect_b32 s48, s50, s48
	s_add_i32 s49, s20, 1
	s_cmp_ge_u32 s48, s7
	s_cselect_b32 s7, s49, s20
	s_xor_b32 s7, s7, s9
	s_sub_i32 s7, s7, s9
	s_mul_i32 s9, s7, s51
	s_lshl_b32 s7, s7, 6
	s_mul_hi_i32 s49, s7, s6
	s_mul_i32 s48, s7, s6
	s_sub_i32 s20, s98, s9
	s_lshl_b64 s[48:49], s[48:49], 2
	s_add_u32 s7, s46, s48
	s_addc_u32 s50, s47, s49
	s_ashr_i32 s9, s8, 31
	s_lshl_b64 s[48:49], s[8:9], 2
	s_add_u32 s7, s7, s48
	s_addc_u32 s9, s50, s49
	s_lshl_b32 s48, s20, 6
	s_ashr_i32 s49, s48, 31
	s_lshl_b64 s[48:49], s[48:49], 2
	s_add_u32 s48, s7, s48
	s_addc_u32 s49, s9, s49
	s_waitcnt vmcnt(5)
	v_lshl_add_u64 v[40:41], s[48:49], 0, v[118:119]
	v_mad_i64_i32 v[0:1], s[48:49], s6, v66, 0
	s_waitcnt vmcnt(4)
	v_mad_i64_i32 v[44:45], s[48:49], s6, v92, 0
	v_lshl_add_u64 v[8:9], v[0:1], 2, v[40:41]
	v_mad_i64_i32 v[0:1], s[48:49], s6, v72, 0
	v_lshl_add_u64 v[120:121], v[44:45], 2, v[40:41]
	v_mad_i64_i32 v[44:45], s[48:49], s6, v94, 0
	v_lshl_add_u64 v[10:11], v[0:1], 2, v[40:41]
	v_lshl_add_u64 v[122:123], v[44:45], 2, v[40:41]
	v_mad_i64_i32 v[44:45], s[48:49], s6, v96, 0
	global_load_dwordx4 v[0:3], v[8:9], off
	global_load_dwordx4 v[4:7], v[10:11], off
	v_mad_i64_i32 v[8:9], s[48:49], s6, v74, 0
	v_mad_i64_i32 v[10:11], s[48:49], s6, v76, 0
	v_mad_i64_i32 v[16:17], s[48:49], s6, v78, 0
	v_mad_i64_i32 v[18:19], s[48:49], s6, v80, 0
	v_mad_i64_i32 v[24:25], s[48:49], s6, v82, 0
	v_mad_i64_i32 v[26:27], s[48:49], s6, v84, 0
	v_mad_i64_i32 v[32:33], s[48:49], s6, v86, 0
	v_mad_i64_i32 v[34:35], s[48:49], s6, v88, 0
	v_mad_i64_i32 v[42:43], s[48:49], s6, v90, 0
	v_lshl_add_u64 v[124:125], v[44:45], 2, v[40:41]
	v_mad_i64_i32 v[44:45], s[48:49], s6, v98, 0
	v_lshl_add_u64 v[8:9], v[8:9], 2, v[40:41]
	v_lshl_add_u64 v[12:13], v[10:11], 2, v[40:41]
	v_lshl_add_u64 v[16:17], v[16:17], 2, v[40:41]
	v_lshl_add_u64 v[20:21], v[18:19], 2, v[40:41]
	v_lshl_add_u64 v[24:25], v[24:25], 2, v[40:41]
	v_lshl_add_u64 v[28:29], v[26:27], 2, v[40:41]
	v_lshl_add_u64 v[32:33], v[32:33], 2, v[40:41]
	v_lshl_add_u64 v[36:37], v[34:35], 2, v[40:41]
	v_lshl_add_u64 v[42:43], v[42:43], 2, v[40:41]
	v_lshl_add_u64 v[126:127], v[44:45], 2, v[40:41]
	v_mad_i64_i32 v[44:45], s[48:49], s6, v100, 0
	global_load_dwordx4 v[8:11], v[8:9], off
	s_nop 0
	global_load_dwordx4 v[12:15], v[12:13], off
	s_nop 0
	global_load_dwordx4 v[16:19], v[16:17], off
	s_nop 0
	global_load_dwordx4 v[20:23], v[20:21], off
	s_nop 0
	global_load_dwordx4 v[24:27], v[24:25], off
	s_nop 0
	global_load_dwordx4 v[28:31], v[28:29], off
	s_nop 0
	global_load_dwordx4 v[32:35], v[32:33], off
	s_nop 0
	global_load_dwordx4 v[36:39], v[36:37], off
	v_lshl_add_u64 v[128:129], v[44:45], 2, v[40:41]
	global_load_dwordx4 v[40:43], v[42:43], off
	s_nop 0
	global_load_dwordx4 v[44:47], v[120:121], off
	global_load_dwordx4 v[48:51], v[122:123], off
	global_load_dwordx4 v[52:55], v[124:125], off
	global_load_dwordx4 v[56:59], v[126:127], off
	global_load_dwordx4 v[60:63], v[128:129], off

; __device__ __forceinline__ void convert_segments(const Args& args, unsigned char* ws, LAS unsigned char* lds, int seg_lo, int seg_hi, int part_lo, int part_hi, int nparts, int wid, int nw, int wave, int lane) {
;     ...
;     for (int sI = seg_lo; sI < seg_hi; ++sI) {
;         const Seg sg = seg_at(sI);
;         const int nblk = sg.ncols / 64, nit = (sg.K / 64) * nblk;
;         const float* W = args.in[sg.in_idx] + (size_t)sg.src_l * sg.K * sg.N;
;         bf16* WT = (bf16*)(ws + WS_W + (size_t)sg.layer * LAYER_W + (size_t)sg.wsub_mib * MiB);
;         const int it_lo = (int)((long)nit * part_lo / nparts), it_hi = (int)((long)nit * part_hi / nparts);
;         int it = it_lo + wid;
;         f32x4 v[16];
;         if (it < it_hi) { const int kb = it / nblk, nb = it - kb * nblk; tr_load(W + (size_t)(64 * kb) * sg.N + sg.scol + 64 * nb, sg.N, v, lane); }
; template <int LAYER>
; __device__ __forceinline__ void layer_steps(const Args& args, LAS unsigned char* lds, const XcdBarrier& bar, const int lo, const int hi, int& step,
;                                             const int G, const int bx, const int vcu, const int gw, const int NGW, const int wave) {
;     ...
;             if (SLOT_ON && G == 256 && bx >= XA_BUSY_WGS) { OPQ; convert_segments(args, ws, lds, SEG_DEFER, SEG_END, layer == 0 ? 0 : 1, layer == 0 ? 1 : 2, 2, (bx - XA_BUSY_WGS) * NWAVES + wave, (G - XA_BUSY_WGS) * NWAVES, wave, olane); }
.LBB0_907:
	s_mul_i32 s7, s25, 40
	s_getpc_b64 s[4:5]
	s_add_u32 s4, s4, __const._Z6seg_ati.segs@rel32@lo+4
	s_addc_u32 s5, s5, __const._Z6seg_ati.segs@rel32@hi+12
	s_mul_hi_u32 s6, s25, 40
	s_add_u32 s14, s4, s7
	s_addc_u32 s15, s5, s6
	s_load_dwordx8 s[4:11], s[14:15], 0x0
	v_lshlrev_b32_e32 v116, 2, v66
	s_waitcnt lgkmcnt(0)
	s_ashr_i32 s12, s9, 31
	s_ashr_i32 s39, s7, 31
	s_lshr_b32 s12, s12, 26
	s_lshr_b32 s26, s39, 26
	s_add_i32 s9, s9, s12
	s_ashr_i32 s44, s9, 6
	s_add_i32 s9, s7, s26
	s_ashr_i32 s27, s4, 31
	s_mov_b32 s26, s4
	s_ashr_i32 s9, s9, 6
	s_lshl_b64 s[26:27], s[26:27], 3
	s_add_u32 s26, s0, s26
	s_addc_u32 s27, s1, s27
	s_load_dwordx2 s[42:43], s[26:27], 0x0
	s_mul_i32 s12, s6, s5
	s_mul_hi_i32 s4, s6, s5
	s_mul_i32 s5, s12, s39
	s_mul_hi_u32 s27, s12, s7
	s_add_i32 s5, s27, s5
	s_mul_i32 s4, s4, s7
	s_add_i32 s5, s5, s4
	s_mul_i32 s4, s12, s7
	s_lshl_b64 s[4:5], s[4:5], 2
	s_mul_i32 s9, s44, s9
	s_waitcnt lgkmcnt(0)
	s_add_u32 s27, s42, s4
	s_addc_u32 s39, s43, s5
	s_lshr_b32 s4, s9, 31
	s_add_i32 s9, s9, s4
	s_mov_b32 s26, s7
	s_movk_i32 s7, 4800
	s_cmp_lt_i32 s18, s7
	s_cselect_b64 s[4:5], -1, 0
	s_cmp_ge_i32 s18, s7
	s_cbranch_scc1 .LBB0_909
	s_abs_i32 s9, s44
	s_waitcnt vmcnt(0)
	v_cvt_f32_u32_e32 v0, s9
	s_sub_i32 s41, 0, s9
	s_ashr_i32 s12, s44, 31
	s_xor_b32 s12, s21, s12
	v_rcp_iflag_f32_e32 v0, v0
	v_mov_b32_e32 v117, v69
	v_mul_f32_e32 v0, 0x4f7ffffe, v0
	v_cvt_u32_f32_e32 v0, v0
	s_nop 0
	v_readfirstlane_b32 s42, v0
	s_mul_i32 s41, s41, s42
	s_mul_hi_u32 s41, s42, s41
	s_add_i32 s42, s42, s41
	s_mul_hi_u32 s41, s22, s42
	s_mul_i32 s42, s41, s9
	s_sub_i32 s42, s22, s42
	s_add_i32 s43, s41, 1
	s_sub_i32 s45, s42, s9
	s_cmp_ge_u32 s42, s9
	s_cselect_b32 s41, s43, s41
	s_cselect_b32 s42, s45, s42
	s_add_i32 s43, s41, 1
	s_cmp_ge_u32 s42, s9
	s_cselect_b32 s9, s43, s41
	s_xor_b32 s9, s9, s12
	s_sub_i32 s9, s9, s12
	s_mul_i32 s12, s9, s44
	s_lshl_b32 s9, s9, 6
	s_mul_hi_i32 s43, s9, s6
	s_mul_i32 s42, s9, s6
	s_sub_i32 s12, s18, s12
	s_lshl_b64 s[42:43], s[42:43], 2
	s_add_u32 s41, s27, s42
	s_addc_u32 s45, s39, s43
	s_ashr_i32 s9, s8, 31
	s_lshl_b64 s[42:43], s[8:9], 2
	s_add_u32 s9, s41, s42
	s_addc_u32 s41, s45, s43
	s_lshl_b32 s42, s12, 6
	s_ashr_i32 s43, s42, 31
	s_lshl_b64 s[42:43], s[42:43], 2
	s_add_u32 s42, s9, s42
	s_addc_u32 s43, s41, s43
	v_lshl_add_u64 v[56:57], s[42:43], 0, v[116:117]
	v_mad_i64_i32 v[0:1], s[42:43], s6, v64, 0
	v_lshl_add_u64 v[8:9], v[0:1], 2, v[56:57]
	v_mad_i64_i32 v[0:1], s[42:43], s6, v70, 0
	v_lshl_add_u64 v[10:11], v[0:1], 2, v[56:57]
	global_load_dwordx4 v[0:3], v[8:9], off
	global_load_dwordx4 v[4:7], v[10:11], off
	v_mad_i64_i32 v[8:9], s[42:43], s6, v72, 0
	v_lshl_add_u64 v[16:17], v[8:9], 2, v[56:57]
	v_mad_i64_i32 v[8:9], s[42:43], s6, v74, 0
	v_lshl_add_u64 v[18:19], v[8:9], 2, v[56:57]
	global_load_dwordx4 v[8:11], v[16:17], off
	global_load_dwordx4 v[12:15], v[18:19], off
	v_mad_i64_i32 v[16:17], s[42:43], s6, v76, 0
	v_lshl_add_u64 v[24:25], v[16:17], 2, v[56:57]
	v_mad_i64_i32 v[16:17], s[42:43], s6, v78, 0
	v_lshl_add_u64 v[26:27], v[16:17], 2, v[56:57]
	global_load_dwordx4 v[16:19], v[24:25], off
	global_load_dwordx4 v[20:23], v[26:27], off
	v_mad_i64_i32 v[24:25], s[42:43], s6, v80, 0
	v_lshl_add_u64 v[32:33], v[24:25], 2, v[56:57]
	v_mad_i64_i32 v[24:25], s[42:43], s6, v82, 0
	v_lshl_add_u64 v[34:35], v[24:25], 2, v[56:57]
	global_load_dwordx4 v[24:27], v[32:33], off
	global_load_dwordx4 v[28:31], v[34:35], off
	v_mad_i64_i32 v[32:33], s[42:43], s6, v84, 0
	v_lshl_add_u64 v[40:41], v[32:33], 2, v[56:57]
	v_mad_i64_i32 v[32:33], s[42:43], s6, v86, 0
	v_lshl_add_u64 v[42:43], v[32:33], 2, v[56:57]
	global_load_dwordx4 v[32:35], v[40:41], off
	global_load_dwordx4 v[36:39], v[42:43], off
	v_mad_i64_i32 v[40:41], s[42:43], s6, v88, 0
	v_lshl_add_u64 v[48:49], v[40:41], 2, v[56:57]
	v_mad_i64_i32 v[40:41], s[42:43], s6, v90, 0
	v_lshl_add_u64 v[50:51], v[40:41], 2, v[56:57]
	global_load_dwordx4 v[40:43], v[48:49], off
	global_load_dwordx4 v[44:47], v[50:51], off
	v_mad_i64_i32 v[48:49], s[42:43], s6, v92, 0
	v_lshl_add_u64 v[58:59], v[48:49], 2, v[56:57]
	v_mad_i64_i32 v[48:49], s[42:43], s6, v94, 0
	v_lshl_add_u64 v[60:61], v[48:49], 2, v[56:57]
	global_load_dwordx4 v[48:51], v[58:59], off
	global_load_dwordx4 v[52:55], v[60:61], off
	v_mad_i64_i32 v[58:59], s[42:43], s6, v96, 0
	v_lshl_add_u64 v[118:119], v[58:59], 2, v[56:57]
	v_mad_i64_i32 v[58:59], s[42:43], s6, v98, 0
	v_lshl_add_u64 v[120:121], v[58:59], 2, v[56:57]
	global_load_dwordx4 v[56:59], v[118:119], off
	global_load_dwordx4 v[60:63], v[120:121], off

; __device__ __forceinline__ void convert_segments(const Args& args, unsigned char* ws, LAS unsigned char* lds, int seg_lo, int seg_hi, int part_lo, int part_hi, int nparts, int wid, int nw, int wave, int lane) {
;     ...
;     for (int sI = seg_lo; sI < seg_hi; ++sI) {
;         const Seg sg = seg_at(sI);
;         const int nblk = sg.ncols / 64, nit = (sg.K / 64) * nblk;
;         const float* W = args.in[sg.in_idx] + (size_t)sg.src_l * sg.K * sg.N;
;         bf16* WT = (bf16*)(ws + WS_W + (size_t)sg.layer * LAYER_W + (size_t)sg.wsub_mib * MiB);
;         const int it_lo = (int)((long)nit * part_lo / nparts), it_hi = (int)((long)nit * part_hi / nparts);
;         int it = it_lo + wid;
;         f32x4 v[16];
;         if (it < it_hi) { const int kb = it / nblk, nb = it - kb * nblk; tr_load(W + (size_t)(64 * kb) * sg.N + sg.scol + 64 * nb, sg.N, v, lane); }
; template <int LAYER>
; __device__ __forceinline__ void layer_steps(const Args& args, LAS unsigned char* lds, const XcdBarrier& bar, const int lo, const int hi, int& step,
;                                             const int G, const int bx, const int vcu, const int gw, const int NGW, const int wave) {
;     ...
;             if (SLOT_ON && G == 256 && bx >= XA_BUSY_WGS) { OPQ; convert_segments(args, ws, lds, SEG_DEFER, SEG_END, layer == 0 ? 0 : 1, layer == 0 ? 1 : 2, 2, (bx - XA_BUSY_WGS) * NWAVES + wave, (G - XA_BUSY_WGS) * NWAVES, wave, olane); }
.LBB0_2119:
	s_mul_i32 s7, s23, 40
	s_getpc_b64 s[4:5]
	s_add_u32 s4, s4, __const._Z6seg_ati.segs@rel32@lo+4
	s_addc_u32 s5, s5, __const._Z6seg_ati.segs@rel32@hi+12
	s_mul_hi_u32 s6, s23, 40
	s_add_u32 s14, s4, s7
	s_addc_u32 s15, s5, s6
	s_load_dwordx8 s[4:11], s[14:15], 0x0
	v_lshlrev_b32_e32 v116, 2, v66
	s_waitcnt lgkmcnt(0)
	s_ashr_i32 s12, s9, 31
	s_ashr_i32 s39, s7, 31
	s_lshr_b32 s12, s12, 26
	s_lshr_b32 s24, s39, 26
	s_add_i32 s9, s9, s12
	s_ashr_i32 s44, s9, 6
	s_add_i32 s9, s7, s24
	s_ashr_i32 s27, s4, 31
	s_mov_b32 s26, s4
	s_ashr_i32 s9, s9, 6
	s_lshl_b64 s[26:27], s[26:27], 3
	s_add_u32 s26, s0, s26
	s_addc_u32 s27, s1, s27
	s_mul_i32 s24, s44, s9
	s_load_dwordx2 s[42:43], s[26:27], 0x0
	s_mul_i32 s9, s6, s5
	s_mul_hi_i32 s4, s6, s5
	s_mul_i32 s5, s9, s39
	s_mul_hi_u32 s12, s9, s7
	s_add_i32 s5, s12, s5
	s_mul_i32 s4, s4, s7
	s_add_i32 s5, s5, s4
	s_mul_i32 s4, s9, s7
	s_lshl_b64 s[4:5], s[4:5], 2
	s_waitcnt lgkmcnt(0)
	s_add_u32 s27, s42, s4
	s_addc_u32 s39, s43, s5
	s_lshr_b32 s4, s24, 31
	s_add_i32 s4, s24, s4
	s_movk_i32 s43, 4800
	s_movk_i32 s24, 9600
	s_add_i32 s26, s18, s43
	s_cmp_lt_i32 s26, s24
	s_mov_b32 s25, s7
	s_cselect_b64 s[4:5], -1, 0
	s_cmp_ge_i32 s26, s24
	s_cbranch_scc1 .LBB0_2121
	s_abs_i32 s7, s44
	s_waitcnt vmcnt(0)
	v_cvt_f32_u32_e32 v0, s7
	s_sub_i32 s41, 0, s7
	s_abs_i32 s12, s26
	s_xor_b32 s9, s26, s44
	v_rcp_iflag_f32_e32 v0, v0
	s_ashr_i32 s9, s9, 31
	v_mov_b32_e32 v117, v69
	v_mul_f32_e32 v0, 0x4f7ffffe, v0
	v_cvt_u32_f32_e32 v0, v0
	s_nop 0
	v_readfirstlane_b32 s42, v0
	s_mul_i32 s41, s41, s42
	s_mul_hi_u32 s41, s42, s41
	s_add_i32 s42, s42, s41
	s_mul_hi_u32 s41, s12, s42
	s_mul_i32 s42, s41, s7
	s_sub_i32 s12, s12, s42
	s_add_i32 s45, s41, 1
	s_sub_i32 s42, s12, s7
	s_cmp_ge_u32 s12, s7
	s_cselect_b32 s41, s45, s41
	s_cselect_b32 s12, s42, s12
	s_add_i32 s42, s41, 1
	s_cmp_ge_u32 s12, s7
	s_cselect_b32 s7, s42, s41
	s_xor_b32 s7, s7, s9
	s_sub_i32 s7, s7, s9
	s_mul_i32 s9, s7, s44
	s_lshl_b32 s7, s7, 6
	s_mul_hi_i32 s47, s7, s6
	s_mul_i32 s46, s7, s6
	s_sub_i32 s12, s26, s9
	s_lshl_b64 s[46:47], s[46:47], 2
	s_add_u32 s7, s27, s46
	s_addc_u32 s41, s39, s47
	s_ashr_i32 s9, s8, 31
	s_lshl_b64 s[46:47], s[8:9], 2
	s_add_u32 s7, s7, s46
	s_addc_u32 s9, s41, s47
	s_lshl_b32 s46, s12, 6
	s_ashr_i32 s47, s46, 31
	s_lshl_b64 s[46:47], s[46:47], 2
	s_add_u32 s46, s7, s46
	s_addc_u32 s47, s9, s47
	v_lshl_add_u64 v[56:57], s[46:47], 0, v[116:117]
	v_mad_i64_i32 v[0:1], s[46:47], s6, v64, 0
	v_lshl_add_u64 v[8:9], v[0:1], 2, v[56:57]
	v_mad_i64_i32 v[0:1], s[46:47], s6, v70, 0
	v_lshl_add_u64 v[10:11], v[0:1], 2, v[56:57]
	global_load_dwordx4 v[0:3], v[8:9], off
	global_load_dwordx4 v[4:7], v[10:11], off
	v_mad_i64_i32 v[8:9], s[46:47], s6, v72, 0
	v_lshl_add_u64 v[16:17], v[8:9], 2, v[56:57]
	v_mad_i64_i32 v[8:9], s[46:47], s6, v74, 0
	v_lshl_add_u64 v[18:19], v[8:9], 2, v[56:57]
	global_load_dwordx4 v[8:11], v[16:17], off
	global_load_dwordx4 v[12:15], v[18:19], off
	v_mad_i64_i32 v[16:17], s[46:47], s6, v76, 0
	v_lshl_add_u64 v[24:25], v[16:17], 2, v[56:57]
	v_mad_i64_i32 v[16:17], s[46:47], s6, v78, 0
	v_lshl_add_u64 v[26:27], v[16:17], 2, v[56:57]
	global_load_dwordx4 v[16:19], v[24:25], off
	global_load_dwordx4 v[20:23], v[26:27], off
	v_mad_i64_i32 v[24:25], s[46:47], s6, v80, 0
	v_lshl_add_u64 v[32:33], v[24:25], 2, v[56:57]
	v_mad_i64_i32 v[24:25], s[46:47], s6, v82, 0
	v_lshl_add_u64 v[34:35], v[24:25], 2, v[56:57]
	global_load_dwordx4 v[24:27], v[32:33], off
	global_load_dwordx4 v[28:31], v[34:35], off
	v_mad_i64_i32 v[32:33], s[46:47], s6, v84, 0
	v_lshl_add_u64 v[40:41], v[32:33], 2, v[56:57]
	v_mad_i64_i32 v[32:33], s[46:47], s6, v86, 0
	v_lshl_add_u64 v[42:43], v[32:33], 2, v[56:57]
	global_load_dwordx4 v[32:35], v[40:41], off
	global_load_dwordx4 v[36:39], v[42:43], off
	v_mad_i64_i32 v[40:41], s[46:47], s6, v88, 0
	v_lshl_add_u64 v[48:49], v[40:41], 2, v[56:57]
	v_mad_i64_i32 v[40:41], s[46:47], s6, v90, 0
	v_lshl_add_u64 v[50:51], v[40:41], 2, v[56:57]
	global_load_dwordx4 v[40:43], v[48:49], off
	global_load_dwordx4 v[44:47], v[50:51], off
	v_mad_i64_i32 v[48:49], s[46:47], s6, v92, 0
	v_lshl_add_u64 v[58:59], v[48:49], 2, v[56:57]
	v_mad_i64_i32 v[48:49], s[46:47], s6, v94, 0
	v_lshl_add_u64 v[60:61], v[48:49], 2, v[56:57]
	global_load_dwordx4 v[48:51], v[58:59], off
	global_load_dwordx4 v[52:55], v[60:61], off
	v_mad_i64_i32 v[58:59], s[46:47], s6, v96, 0
	v_lshl_add_u64 v[118:119], v[58:59], 2, v[56:57]
	v_mad_i64_i32 v[58:59], s[46:47], s6, v98, 0
	v_lshl_add_u64 v[120:121], v[58:59], 2, v[56:57]
	global_load_dwordx4 v[56:59], v[118:119], off
	global_load_dwordx4 v[60:63], v[120:121], off
